# SO7 + s_setprio 2 for the chunk waves (0-3) during the chunk loop (they are the critical path of the fifth segment now)
# baseline (speedup 1.0000x reference)
.LBB0_438:
	s_andn2_b64 vcc, exec, s[90:91]
	s_cbranch_vccnz .LBB0_446
	s_setprio 2
	v_and_b32_e32 v38, 0x3e0, v135
	s_movk_i32 s10, 0xc00
	v_and_b32_e32 v37, 0x3e0, v133
	v_add3_u32 v86, v38, v127, s10
	s_movk_i32 s10, 0x800
	v_lshl_add_u32 v82, v128, 5, v127
	v_and_b32_e32 v36, 0x3e0, v131
	v_lshl_add_u32 v34, v125, 8, s35
	v_add3_u32 v87, v37, v127, s10
	s_movk_i32 s10, 0x400
	v_add_lshl_u32 v83, v34, v128, 1
	v_add_u32_e32 v84, 0x1c800, v82
	v_add_u32_e32 v85, s70, v82
	v_add3_u32 v88, v36, v127, s10
	s_mov_b32 s14, 0
	v_lshlrev_b32_e32 v106, 1, v128
	v_mov_b32_e32 v89, v127
	v_mov_b32_e32 v90, v82
	v_lshl_add_u32 v66, v134, 12, v106
	v_add_u32_e32 v68, 0x1000, v66
	v_add_u32_e32 v70, 0x2000, v66
	v_add_u32_e32 v72, 0x3000, v66
	v_add_u32_e32 v74, 0x8000, v66
	v_add_u32_e32 v76, 0x9000, v66
	v_add_u32_e32 v78, 0xa000, v66
	v_add_u32_e32 v80, 0xb000, v66
	s_branch .LBB0_441

.LBB0_445:
	v_add_u32_e32 v34, 0, v127
	v_add_u32_e32 v62, 0x22e00, v34
	ds_read_b128 v[34:37], v62
	ds_read_b128 v[38:41], v62 offset:32
	ds_read_b128 v[42:45], v62 offset:64
	ds_read_b128 v[46:49], v62 offset:96
	ds_read_b128 v[50:53], v62 offset:128
	ds_read_b128 v[54:57], v62 offset:160
	ds_read_b128 v[58:61], v62 offset:192
	ds_read_b128 v[62:65], v62 offset:224
	s_waitcnt lgkmcnt(4)
	v_pk_mul_f32 v[16:17], v[16:17], v[48:49]
	v_pk_mul_f32 v[14:15], v[14:15], v[46:47]
	v_pk_mul_f32 v[12:13], v[12:13], v[44:45]
	v_pk_mul_f32 v[10:11], v[10:11], v[42:43]
	v_pk_mul_f32 v[8:9], v[8:9], v[40:41]
	v_pk_mul_f32 v[6:7], v[6:7], v[38:39]
	v_pk_mul_f32 v[4:5], v[4:5], v[36:37]
	v_pk_mul_f32 v[2:3], v[2:3], v[34:35]
	s_waitcnt lgkmcnt(0)
	v_pk_mul_f32 v[32:33], v[32:33], v[64:65]
	v_pk_mul_f32 v[30:31], v[30:31], v[62:63]
	v_pk_mul_f32 v[28:29], v[28:29], v[60:61]
	v_pk_mul_f32 v[26:27], v[26:27], v[58:59]
	v_pk_mul_f32 v[24:25], v[24:25], v[56:57]
	v_pk_mul_f32 v[22:23], v[22:23], v[54:55]
	v_pk_mul_f32 v[20:21], v[20:21], v[52:53]
	v_pk_mul_f32 v[18:19], v[18:19], v[50:51]
	s_setprio 0
